# attention fast path: next-tile LDS staging writes moved before the last PV MFMA group (overlap with matrix work)
# baseline (speedup 1.0000x reference)
.LBB0_589:
	s_bitcmp1_b32 s70, 0
	v_cvt_f32_i32_e32 v130, v190
	s_cselect_b32 s1, 0x8200, 0
	s_addk_i32 s1, 0x100
	s_cmp_eq_u32 s4, s70
	s_cbranch_scc1 .Latt_diag
	v_add_u32_e32 v127, s1, v166
	ds_read_b128 v[198:201], v127
	ds_read_b128 v[222:225], v186
	ds_read_b128 v[202:205], v127 offset:2080
	ds_read_b128 v[226:229], v186 offset:4128
	ds_read_b128 v[206:209], v127 offset:4160
	ds_read_b128 v[230:233], v186 offset:8256
	ds_read_b128 v[210:213], v127 offset:6240
	ds_read_b128 v[234:237], v186 offset:12384
	ds_read_b128 v[214:217], v127 offset:512
	ds_read_b128 v[218:221], v127 offset:2592
	v_fma_f32 v192, -v129, v130, -v188
	v_mov_b32_e32 v80, v129
	v_add3_u32 v191, s1, v167, v168
	v_fma_f32 v64, 0, v80, v192
	v_add_f32_e32 v65, v80, v192
	v_pk_fma_f32 v[66:67], v[80:81], s[84:85], v[192:193] op_sel_hi:[0,1,0]
	v_pk_fma_f32 v[68:69], v[80:81], s[86:87], v[192:193] op_sel_hi:[0,1,0]
	v_pk_fma_f32 v[70:71], v[80:81], s[88:89], v[192:193] op_sel_hi:[0,1,0]
	v_pk_fma_f32 v[72:73], v[80:81], s[90:91], v[192:193] op_sel_hi:[0,1,0]
	v_pk_fma_f32 v[74:75], v[80:81], s[92:93], v[192:193] op_sel_hi:[0,1,0]
	v_pk_fma_f32 v[76:77], v[80:81], s[94:95], v[192:193] op_sel_hi:[0,1,0]
	v_pk_fma_f32 v[78:79], v[80:81], s[96:97], v[192:193] op_sel_hi:[0,1,0]
	v_pk_fma_f32 v[94:95], v[80:81], s[22:23], v[192:193] op_sel_hi:[0,1,0]
	v_pk_fma_f32 v[92:93], v[80:81], s[74:75], v[192:193] op_sel_hi:[0,1,0]
	v_pk_fma_f32 v[90:91], v[80:81], s[76:77], v[192:193] op_sel_hi:[0,1,0]
	v_pk_fma_f32 v[88:89], v[80:81], s[24:25], v[192:193] op_sel_hi:[0,1,0]
	v_pk_fma_f32 v[86:87], v[80:81], s[26:27], v[192:193] op_sel_hi:[0,1,0]
	v_pk_fma_f32 v[84:85], v[80:81], s[72:73], v[192:193] op_sel_hi:[0,1,0]
	v_pk_fma_f32 v[82:83], v[80:81], s[18:19], v[192:193] op_sel_hi:[0,1,0]
	v_pk_fma_f32 v[80:81], v[80:81], s[34:35], v[192:193] op_sel_hi:[0,1,0]
	ds_read_b128 v[192:195], v127 offset:4672
	s_waitcnt lgkmcnt(9)
	v_mfma_f32_32x32x16_bf16 v[64:79], v[198:201], v[222:225], v[64:79]
	ds_read_b128 v[198:201], v127 offset:6752
	s_waitcnt lgkmcnt(8)
	v_mfma_f32_32x32x16_bf16 v[64:79], v[202:205], v[226:229], v[64:79]
	s_waitcnt lgkmcnt(6)
	v_mfma_f32_32x32x16_bf16 v[64:79], v[206:209], v[230:233], v[64:79]
	s_waitcnt lgkmcnt(4)
	v_mfma_f32_32x32x16_bf16 v[64:79], v[210:213], v[234:237], v[64:79]
	ds_read_b128 v[202:205], v191 offset:16640
	ds_read_b128 v[206:209], v191 offset:17152
	ds_read_b128 v[210:213], v191 offset:17664
	s_waitcnt lgkmcnt(6)
	v_mfma_f32_32x32x16_bf16 v[80:95], v[214:217], v[222:225], v[80:95]
	s_waitcnt lgkmcnt(5)
	v_mfma_f32_32x32x16_bf16 v[80:95], v[218:221], v[226:229], v[80:95]
	s_waitcnt lgkmcnt(4)
	v_mfma_f32_32x32x16_bf16 v[80:95], v[192:195], v[230:233], v[80:95]
	s_waitcnt lgkmcnt(3)
	v_mfma_f32_32x32x16_bf16 v[80:95], v[198:201], v[234:237], v[80:95]
	ds_read_b128 v[214:217], v191 offset:18176
	ds_read_b128 v[218:221], v191 offset:20768
	ds_read_b128 v[192:195], v191 offset:21280
	ds_read_b128 v[198:201], v191 offset:21792
	ds_read_b128 v[222:225], v191 offset:22304
	ds_read_b128 v[226:229], v191 offset:24896
	ds_read_b128 v[230:233], v191 offset:25408
	ds_read_b128 v[234:237], v191 offset:25920
	v_exp_f32_e32 v64, v64
	v_exp_f32_e32 v65, v65
	v_exp_f32_e32 v66, v66
	v_exp_f32_e32 v67, v67
	v_exp_f32_e32 v68, v68
	v_exp_f32_e32 v69, v69
	v_exp_f32_e32 v70, v70
	v_exp_f32_e32 v71, v71
	v_add_f32_e32 v130, v64, v65
	v_add_f32_e32 v130, v130, v66
	v_add_f32_e32 v130, v130, v67
	v_add_f32_e32 v130, v130, v68
	v_add_f32_e32 v130, v130, v69
	v_add_f32_e32 v130, v130, v70
	v_add_f32_e32 v130, v130, v71
	v_cvt_pk_bf16_f32 v64, v64, v65
	v_cvt_pk_bf16_f32 v65, v66, v67
	v_cvt_pk_bf16_f32 v66, v68, v69
	v_cvt_pk_bf16_f32 v67, v70, v71
	s_waitcnt lgkmcnt(10)
	v_exp_f32_e32 v72, v72
	v_mfma_f32_32x32x16_bf16 v[48:63], v[202:205], v[64:67], v[48:63]
	v_exp_f32_e32 v73, v73
	v_exp_f32_e32 v74, v74
	v_add_f32_e32 v130, v130, v72
	v_add_f32_e32 v130, v130, v73
	s_waitcnt lgkmcnt(9)
	v_mfma_f32_32x32x16_bf16 v[32:47], v[206:209], v[64:67], v[32:47]
	v_exp_f32_e32 v75, v75
	v_exp_f32_e32 v76, v76
	v_cvt_pk_bf16_f32 v68, v72, v73
	v_add_f32_e32 v130, v130, v74
	s_waitcnt lgkmcnt(8)
	v_mfma_f32_32x32x16_bf16 v[16:31], v[210:213], v[64:67], v[16:31]
	v_exp_f32_e32 v77, v77
	v_exp_f32_e32 v78, v78
	v_cvt_pk_bf16_f32 v69, v74, v75
	v_add_f32_e32 v130, v130, v75
	v_add_f32_e32 v130, v130, v76
	s_waitcnt lgkmcnt(7)
	v_mfma_f32_32x32x16_bf16 v[0:15], v[214:217], v[64:67], v[0:15]
	ds_read_b128 v[202:205], v191 offset:26432
	ds_read_b128 v[206:209], v191 offset:29024
	ds_read_b128 v[210:213], v191 offset:29536
	ds_read_b128 v[214:217], v191 offset:30048
	v_exp_f32_e32 v79, v79
	v_cvt_pk_bf16_f32 v70, v76, v77
	v_add_f32_e32 v130, v130, v77
	v_add_f32_e32 v130, v130, v78
	v_add_f32_e32 v130, v130, v79
	v_cvt_pk_bf16_f32 v71, v78, v79
	s_waitcnt lgkmcnt(10)
	v_exp_f32_e32 v80, v80
	v_mfma_f32_32x32x16_bf16 v[48:63], v[218:221], v[68:71], v[48:63]
	v_exp_f32_e32 v81, v81
	v_exp_f32_e32 v82, v82
	v_add_f32_e32 v130, v130, v80
	v_add_f32_e32 v130, v130, v81
	s_waitcnt lgkmcnt(9)
	v_mfma_f32_32x32x16_bf16 v[32:47], v[192:195], v[68:71], v[32:47]
	v_exp_f32_e32 v83, v83
	v_exp_f32_e32 v84, v84
	v_cvt_pk_bf16_f32 v72, v80, v81
	v_add_f32_e32 v130, v130, v82
	s_waitcnt lgkmcnt(8)
	v_mfma_f32_32x32x16_bf16 v[16:31], v[198:201], v[68:71], v[16:31]
	v_exp_f32_e32 v85, v85
	v_exp_f32_e32 v86, v86
	v_cvt_pk_bf16_f32 v73, v82, v83
	v_add_f32_e32 v130, v130, v83
	v_add_f32_e32 v130, v130, v84
	s_waitcnt lgkmcnt(7)
	v_mfma_f32_32x32x16_bf16 v[0:15], v[222:225], v[68:71], v[0:15]
	ds_read_b128 v[218:221], v191 offset:30560
	v_exp_f32_e32 v87, v87
	v_cvt_pk_bf16_f32 v74, v84, v85
	v_add_f32_e32 v130, v130, v85
	v_add_f32_e32 v130, v130, v86
	v_add_f32_e32 v130, v130, v87
	v_cvt_pk_bf16_f32 v75, v86, v87
	s_waitcnt lgkmcnt(7)
	v_exp_f32_e32 v88, v88
	v_mfma_f32_32x32x16_bf16 v[48:63], v[226:229], v[72:75], v[48:63]
	v_exp_f32_e32 v89, v89
	v_exp_f32_e32 v90, v90
	v_add_f32_e32 v130, v130, v88
	v_add_f32_e32 v130, v130, v89
	s_waitcnt lgkmcnt(6)
	v_mfma_f32_32x32x16_bf16 v[32:47], v[230:233], v[72:75], v[32:47]
	v_exp_f32_e32 v91, v91
	v_exp_f32_e32 v92, v92
	v_cvt_pk_bf16_f32 v76, v88, v89
	v_add_f32_e32 v130, v130, v90
	s_waitcnt lgkmcnt(5)
	v_mfma_f32_32x32x16_bf16 v[16:31], v[234:237], v[72:75], v[16:31]
	v_exp_f32_e32 v93, v93
	v_exp_f32_e32 v94, v94
	v_cvt_pk_bf16_f32 v77, v90, v91
	v_add_f32_e32 v130, v130, v91
	v_add_f32_e32 v130, v130, v92
	s_waitcnt lgkmcnt(4)
	v_mfma_f32_32x32x16_bf16 v[0:15], v[202:205], v[72:75], v[0:15]
	v_exp_f32_e32 v95, v95
	v_cvt_pk_bf16_f32 v78, v92, v93
	v_add_f32_e32 v130, v130, v93
	v_add_f32_e32 v130, v130, v94
	v_add_f32_e32 v130, v130, v95
	v_cvt_pk_bf16_f32 v79, v94, v95
	s_and_b64 vcc, exec, s[10:11]
	s_cbranch_vccz .Latt_nostore
	s_sub_i32 s1, 0x8400, s1
	v_add_u32_e32 v127, s1, v170
	v_add_u32_e32 v191, s1, v172
	s_waitcnt vmcnt(3)
	ds_write_b128 v127, v[96:99]
	s_waitcnt vmcnt(2)
	ds_write_b128 v127, v[100:103] offset:64
	s_waitcnt vmcnt(1)
	ds_write_b128 v191, v[104:107] offset:16640
	s_waitcnt vmcnt(0)
	ds_write_b128 v191, v[108:111] offset:16768
	s_waitcnt lgkmcnt(7)
	v_mfma_f32_32x32x16_bf16 v[48:63], v[206:209], v[76:79], v[48:63]
	s_waitcnt lgkmcnt(6)
	v_mfma_f32_32x32x16_bf16 v[32:47], v[210:213], v[76:79], v[32:47]
	s_waitcnt lgkmcnt(5)
	v_mfma_f32_32x32x16_bf16 v[16:31], v[214:217], v[76:79], v[16:31]
	s_waitcnt lgkmcnt(4)
	v_mfma_f32_32x32x16_bf16 v[0:15], v[218:221], v[76:79], v[0:15]
	v_add_f32_e32 v150, v150, v130
	s_add_i32 s70, s70, 1
	s_branch .LBB0_584
.Latt_nostore:
	s_waitcnt lgkmcnt(3)
	v_mfma_f32_32x32x16_bf16 v[48:63], v[206:209], v[76:79], v[48:63]
	s_waitcnt lgkmcnt(2)
	v_mfma_f32_32x32x16_bf16 v[32:47], v[210:213], v[76:79], v[32:47]
	s_waitcnt lgkmcnt(1)
	v_mfma_f32_32x32x16_bf16 v[16:31], v[214:217], v[76:79], v[16:31]
	s_waitcnt lgkmcnt(0)
	v_mfma_f32_32x32x16_bf16 v[0:15], v[218:221], v[76:79], v[0:15]
	v_add_f32_e32 v150, v150, v130
	s_add_i32 s70, s70, 1
	s_branch .LBB0_584
